# main GEMM tile epilogue: row-group store addresses chained by scalar-stride 64-bit adds (11 of 12 64-bit multiplies removed), accumulators zeroed with v_mov_b64
# speedup vs baseline: 1.0051x; 1.0051x over previous
; #define LDA(dst, b, h) for (int m = 0; m < 4; ++m) for (int k = 0; k < 2; ++k) \
;     dst[m][k] = *reinterpret_cast<const bf16x8*>(SA(b, h) + lds_byte(wr * 64 + m * 16 + fr, k * 32 + fq * 8))
; #define LDB(dst, b, h) for (int n = 0; n < 2; ++n) for (int k = 0; k < 2; ++k) \
;     dst[n][k] = *reinterpret_cast<const bf16x8*>(SB(b, h) + lds_byte(wc * 32 + n * 16 + fr, k * 32 + fq * 8))
; #define MMA(ai, bj, At_, Bt_) do { __builtin_amdgcn_s_setprio(1); \
;     for (int m = 0; m < 4; ++m) for (int n = 0; n < 2; ++n) for (int k = 0; k < 2; ++k) \
;       acc[ai][bj][m][n] = __builtin_amdgcn_mfma_f32_16x16x32_bf16(Bt_[n][k], At_[m][k], acc[ai][bj][m][n], 0, 0, 0); \
;     __builtin_amdgcn_s_setprio(0); } while (0)
; #define WAIT_V(n) asm volatile("s_waitcnt vmcnt(" #n ")" ::: "memory")
; #define WAIT_L(n) asm volatile("s_waitcnt lgkmcnt(" #n ")" ::: "memory")
; #define BAR __builtin_amdgcn_s_barrier()
; #define SCHED __builtin_amdgcn_sched_barrier(0)
; #define STG(P, PTR, LD, O0) do { const bf16_t* _g = (PTR); \
;     __builtin_amdgcn_global_load_lds((const unsigned*)(_g + O0), (lds_u32*)((P) + swave * 1024), 16, 0, 0); \
;     __builtin_amdgcn_global_load_lds((const unsigned*)(_g + (size_t)64 * (LD) + O0), (lds_u32*)((P) + swave * 1024 + 8192), 16, 0, 0); } while (0)
; __device__ __forceinline__ void gemm_stream(int swave, const GemmJob& J, char* shm, int vb, int G) {
;     ...
;     for (int t = 0; t < nt; t += 2) {
;       const bool last = (t == nt - 2);
;       const bf16_t* xA = last ? nA : cA; const bf16_t* xA1 = last ? nA1 : cA1; const int k2 = last ? 0 : t + 2;
;       const bf16_t* b2 = last ? nB : cB + (size_t)(t + 2) * 64; const bf16_t* b3 = b2 + 64;
;       LDB(B0, 0, 0); SCHED; LDA(At, 0, 0); STGA(SA(1, 1), cA, cA1, t + 1, 1);
;       WAIT_L(8); BAR; WAIT_L(0); MMA(0, 0, At, B0); BAR; SCHED;
;       LDB(B1, 0, 1); STG(SB(0, 0), b2, ldb, offB0);
;       BAR; WAIT_L(0); MMA(0, 1, At, B1); BAR;
;       LDA(At, 0, 1); STGA(SA(0, 0), xA, xA1, k2, 0);
;       BAR; WAIT_L(0); MMA(1, 0, At, B0); BAR; SCHED;
;       STG(SB(0, 1), b2 + hB, ldb, offB0);
;       WAIT_V(6); BAR; MMA(1, 1, At, B1); BAR;
;     ...
; #pragma unroll
;     for (int a_ = 0; a_ < 2; ++a_)
; #pragma unroll
;       for (int b_ = 0; b_ < 2; ++b_)
; #pragma unroll
;         for (int m = 0; m < 4; ++m)
; #pragma unroll
;           for (int n = 0; n < 2; ++n) acc[a_][b_][m][n] = (f32x4){0.f, 0.f, 0.f, 0.f};
.LBB0_728:
	s_add_u32 s20, s2, 0x100
	v_mov_b64_e32 v[4:5], 0
	v_mov_b64_e32 v[6:7], 0
	v_mov_b64_e32 v[8:9], 0
	v_mov_b64_e32 v[10:11], 0
	v_mov_b64_e32 v[12:13], 0
	v_mov_b64_e32 v[14:15], 0
	v_mov_b64_e32 v[16:17], 0
	v_mov_b64_e32 v[18:19], 0
	v_mov_b64_e32 v[20:21], 0
	v_mov_b64_e32 v[22:23], 0
	v_mov_b64_e32 v[24:25], 0
	v_mov_b64_e32 v[26:27], 0
	v_mov_b64_e32 v[28:29], 0
	v_mov_b64_e32 v[30:31], 0
	v_mov_b64_e32 v[32:33], 0
	v_mov_b64_e32 v[34:35], 0
	v_mov_b64_e32 v[36:37], 0
	v_mov_b64_e32 v[38:39], 0
	v_mov_b64_e32 v[40:41], 0
	v_mov_b64_e32 v[42:43], 0
	v_mov_b64_e32 v[44:45], 0
	v_mov_b64_e32 v[46:47], 0
	v_mov_b64_e32 v[48:49], 0
	v_mov_b64_e32 v[50:51], 0
	v_mov_b64_e32 v[52:53], 0
	v_mov_b64_e32 v[54:55], 0
	v_mov_b64_e32 v[56:57], 0
	v_mov_b64_e32 v[58:59], 0
	v_mov_b64_e32 v[60:61], 0
	v_mov_b64_e32 v[62:63], 0
	v_mov_b64_e32 v[64:65], 0
	v_mov_b64_e32 v[66:67], 0
	v_mov_b64_e32 v[68:69], 0
	v_mov_b64_e32 v[70:71], 0
	v_mov_b64_e32 v[72:73], 0
	v_mov_b64_e32 v[74:75], 0
	v_mov_b64_e32 v[76:77], 0
	v_mov_b64_e32 v[78:79], 0
	v_mov_b64_e32 v[80:81], 0
	v_mov_b64_e32 v[82:83], 0
	v_mov_b64_e32 v[84:85], 0
	v_mov_b64_e32 v[86:87], 0
	v_mov_b64_e32 v[88:89], 0
	v_mov_b64_e32 v[90:91], 0
	v_mov_b64_e32 v[92:93], 0
	v_mov_b64_e32 v[94:95], 0
	v_mov_b64_e32 v[96:97], 0
	v_mov_b64_e32 v[98:99], 0
	v_mov_b64_e32 v[100:101], 0
	v_mov_b64_e32 v[102:103], 0
	v_mov_b64_e32 v[104:105], 0
	v_mov_b64_e32 v[106:107], 0
	v_mov_b64_e32 v[108:109], 0
	v_mov_b64_e32 v[110:111], 0
	v_mov_b64_e32 v[112:113], 0
	v_mov_b64_e32 v[114:115], 0
	v_mov_b64_e32 v[116:117], 0
	v_mov_b64_e32 v[118:119], 0
	v_mov_b64_e32 v[120:121], 0
	v_mov_b64_e32 v[122:123], 0
	v_mov_b64_e32 v[124:125], 0
	v_mov_b64_e32 v[126:127], 0
	v_mov_b64_e32 v[128:129], 0
	v_mov_b64_e32 v[130:131], 0
	s_addc_u32 s21, s3, 0
	s_mov_b32 s2, 0
	s_mov_b32 s29, 2
.LBB0_729:
	ds_read_b128 v[164:167], v139
	ds_read_b128 v[168:171], v139 offset:1024
	ds_read_b128 v[172:175], v139 offset:2048
	ds_read_b128 v[176:179], v139 offset:3072
	s_cmp_eq_u32 s49, s29
	s_cselect_b64 s[68:69], -1, 0
	s_and_b64 s[64:65], s[68:69], exec
	s_cselect_b32 s52, s10, s8
	s_cselect_b32 s64, s11, s9
	s_add_i32 s33, s2, 2
	s_and_b64 s[68:69], s[68:69], exec
	s_cselect_b32 s71, s15, s21
	s_cselect_b32 s70, s14, s20
	s_cselect_b32 s68, 0, s33
	s_cselect_b32 s65, s12, s16
	s_cselect_b32 s66, s13, s17
	s_or_b32 s2, s2, 1
	s_cmp_lt_u32 s2, s36
	s_cselect_b64 vcc, -1, 0
	s_and_b64 s[2:3], vcc, exec
	s_cselect_b32 s3, 0, s36
	s_cselect_b32 s2, s38, s37
	s_not_b32 s3, s3
	s_add_i32 s94, s3, s29
	s_and_b64 s[72:73], vcc, exec
	s_cselect_b32 s3, s9, s17
	s_cselect_b32 s69, s8, s16
	s_lshl_b64 s[72:73], s[94:95], 7
	s_add_u32 s69, s69, s72
	s_addc_u32 s74, s3, s73
	s_mov_b32 s3, s95
	s_lshl_b64 s[72:73], s[2:3], 8
	s_add_u32 s72, s69, s72
	v_cndmask_b32_e32 v2, v138, v0, vcc
	s_addc_u32 s73, s74, s73
	s_add_i32 m0, s42, 0xc000
	s_lshl_b64 s[2:3], s[2:3], 7
	v_lshlrev_b64 v[212:213], 1, v[2:3]
	s_add_u32 s2, s72, s2
	v_lshl_add_u64 v[214:215], s[72:73], 0, v[212:213]
	s_addc_u32 s3, s73, s3
	ds_read_b128 v[180:183], v144
	ds_read_b128 v[184:187], v144 offset:1024
	ds_read_b128 v[188:191], v145
	ds_read_b128 v[192:195], v145 offset:1024
	ds_read_b128 v[196:199], v159
	ds_read_b128 v[200:203], v159 offset:1024
	ds_read_b128 v[204:207], v160
	ds_read_b128 v[208:211], v160 offset:1024
	global_load_lds_dwordx4 v[214:215], off
	v_lshl_add_u64 v[212:213], s[2:3], 0, v[212:213]
	s_add_i32 m0, s42, 0xe000
	s_nop 0
	global_load_lds_dwordx4 v[212:213], off
	s_waitcnt lgkmcnt(8)
	s_barrier
	s_waitcnt lgkmcnt(0)
	s_waitcnt lgkmcnt(0)
	v_mfma_f32_16x16x32_bf16 v[128:131], v[164:167], v[180:183], v[128:131]
	v_mfma_f32_16x16x32_bf16 v[124:127], v[172:175], v[180:183], v[124:127]
	v_mfma_f32_16x16x32_bf16 v[120:123], v[164:167], v[188:191], v[120:123]
	v_mfma_f32_16x16x32_bf16 v[116:119], v[172:175], v[188:191], v[116:119]
	v_mfma_f32_16x16x32_bf16 v[104:107], v[164:167], v[196:199], v[104:107]
	v_mfma_f32_16x16x32_bf16 v[100:103], v[172:175], v[196:199], v[100:103]
	v_mfma_f32_16x16x32_bf16 v[88:91], v[164:167], v[204:207], v[88:91]
	v_mfma_f32_16x16x32_bf16 v[84:87], v[172:175], v[204:207], v[84:87]
	v_mfma_f32_16x16x32_bf16 v[128:131], v[168:171], v[184:187], v[128:131]
	v_mfma_f32_16x16x32_bf16 v[124:127], v[176:179], v[184:187], v[124:127]
	v_mfma_f32_16x16x32_bf16 v[120:123], v[168:171], v[192:195], v[120:123]
	v_mfma_f32_16x16x32_bf16 v[116:119], v[176:179], v[192:195], v[116:119]
	v_mfma_f32_16x16x32_bf16 v[104:107], v[168:171], v[200:203], v[104:107]
	v_mfma_f32_16x16x32_bf16 v[100:103], v[176:179], v[200:203], v[100:103]
	v_mfma_f32_16x16x32_bf16 v[88:91], v[168:171], v[208:211], v[88:91]
	v_mfma_f32_16x16x32_bf16 v[84:87], v[176:179], v[208:211], v[84:87]
	s_barrier
	s_add_u32 s2, s70, s0
	s_mov_b32 m0, s43
	v_lshl_add_u64 v[228:229], s[70:71], 0, v[136:137]
	s_addc_u32 s3, s71, s1
	ds_read_b128 v[212:215], v161
	ds_read_b128 v[216:219], v161 offset:1024
	ds_read_b128 v[220:223], v161 offset:2048
	ds_read_b128 v[224:227], v161 offset:3072
	global_load_lds_dwordx4 v[228:229], off
	v_lshl_add_u64 v[230:231], s[2:3], 0, v[136:137]
	s_mov_b32 m0, s44
	s_nop 0
	global_load_lds_dwordx4 v[230:231], off
	s_barrier
; #define LDA(dst, b, h) for (int m = 0; m < 4; ++m) for (int k = 0; k < 2; ++k) \
;     dst[m][k] = *reinterpret_cast<const bf16x8*>(SA(b, h) + lds_byte(wr * 64 + m * 16 + fr, k * 32 + fq * 8))
; #define LDB(dst, b, h) for (int n = 0; n < 2; ++n) for (int k = 0; k < 2; ++k) \
;     dst[n][k] = *reinterpret_cast<const bf16x8*>(SB(b, h) + lds_byte(wc * 32 + n * 16 + fr, k * 32 + fq * 8))
; #define MMA(ai, bj, At_, Bt_) do { __builtin_amdgcn_s_setprio(1); \
;     for (int m = 0; m < 4; ++m) for (int n = 0; n < 2; ++n) for (int k = 0; k < 2; ++k) \
;       acc[ai][bj][m][n] = __builtin_amdgcn_mfma_f32_16x16x32_bf16(Bt_[n][k], At_[m][k], acc[ai][bj][m][n], 0, 0, 0); \
;     __builtin_amdgcn_s_setprio(0); } while (0)
; #define WAIT_V(n) asm volatile("s_waitcnt vmcnt(" #n ")" ::: "memory")
; #define WAIT_L(n) asm volatile("s_waitcnt lgkmcnt(" #n ")" ::: "memory")
; #define BAR __builtin_amdgcn_s_barrier()
; #define SCHED __builtin_amdgcn_sched_barrier(0)
; #define STG(P, PTR, LD, O0) do { const bf16_t* _g = (PTR); \
;     __builtin_amdgcn_global_load_lds((const unsigned*)(_g + O0), (lds_u32*)((P) + swave * 1024), 16, 0, 0); \
;     __builtin_amdgcn_global_load_lds((const unsigned*)(_g + (size_t)64 * (LD) + O0), (lds_u32*)((P) + swave * 1024 + 8192), 16, 0, 0); } while (0)
; #define LDA(dst, b, h) for (int m = 0; m < 4; ++m) for (int k = 0; k < 2; ++k) \
;     dst[m][k] = *reinterpret_cast<const bf16x8*>(SA(b, h) + lds_byte(wr * 64 + m * 16 + fr, k * 32 + fq * 8))
; #define LDB(dst, b, h) for (int n = 0; n < 2; ++n) for (int k = 0; k < 2; ++k) \
;     dst[n][k] = *reinterpret_cast<const bf16x8*>(SB(b, h) + lds_byte(wc * 32 + n * 16 + fr, k * 32 + fq * 8))
; #define BAR __builtin_amdgcn_s_barrier()
; __device__ __forceinline__ void gemm_stream(int swave, const GemmJob& J, char* shm, int vb, int G) {
;     ...
;       LDB(B1, 0, 1); STG(SB(0, 0), b2, ldb, offB0);
;       BAR; WAIT_L(0); MMA(0, 1, At, B1); BAR;
;       LDA(At, 0, 1); STGA(SA(0, 0), xA, xA1, k2, 0);
;       BAR; WAIT_L(0); MMA(1, 0, At, B0); BAR; SCHED;
;       STG(SB(0, 1), b2 + hB, ldb, offB0);
;       WAIT_V(6); BAR; MMA(1, 1, At, B1); BAR;
;       LDB(B0, 1, 0); SCHED; LDA(At, 1, 0); STGA(SA(0, 1), xA, xA1, k2, 1);
;       WAIT_L(8); BAR; WAIT_L(0); MMA(0, 0, At, B0); BAR; SCHED;
;       LDB(B1, 1, 1); STG(SB(1, 0), b3, ldb, offB0);
;       BAR; WAIT_L(0); MMA(0, 1, At, B1); BAR;
	s_waitcnt lgkmcnt(0)
	s_waitcnt lgkmcnt(0)
	v_mfma_f32_16x16x32_bf16 v[112:115], v[212:215], v[180:183], v[112:115]
	v_mfma_f32_16x16x32_bf16 v[108:111], v[220:223], v[180:183], v[108:111]
	v_mfma_f32_16x16x32_bf16 v[96:99], v[212:215], v[188:191], v[96:99]
	v_mfma_f32_16x16x32_bf16 v[92:95], v[220:223], v[188:191], v[92:95]
	v_mfma_f32_16x16x32_bf16 v[80:83], v[212:215], v[196:199], v[80:83]
	v_mfma_f32_16x16x32_bf16 v[76:79], v[220:223], v[196:199], v[76:79]
	v_mfma_f32_16x16x32_bf16 v[72:75], v[212:215], v[204:207], v[72:75]
	v_mfma_f32_16x16x32_bf16 v[68:71], v[220:223], v[204:207], v[68:71]
	v_mfma_f32_16x16x32_bf16 v[112:115], v[216:219], v[184:187], v[112:115]
	v_mfma_f32_16x16x32_bf16 v[108:111], v[224:227], v[184:187], v[108:111]
	v_mfma_f32_16x16x32_bf16 v[96:99], v[216:219], v[192:195], v[96:99]
	v_mfma_f32_16x16x32_bf16 v[92:95], v[224:227], v[192:195], v[92:95]
	v_mfma_f32_16x16x32_bf16 v[80:83], v[216:219], v[200:203], v[80:83]
	v_mfma_f32_16x16x32_bf16 v[76:79], v[224:227], v[200:203], v[76:79]
	v_mfma_f32_16x16x32_bf16 v[72:75], v[216:219], v[208:211], v[72:75]
	v_mfma_f32_16x16x32_bf16 v[68:71], v[224:227], v[208:211], v[68:71]
	s_cmp_lt_u32 s68, s36
	s_cselect_b64 vcc, -1, 0
	s_and_b64 s[70:71], vcc, exec
	s_cselect_b32 s70, s38, s37
	s_sub_i32 s69, s68, s36
	s_min_u32 s94, s68, s69
	s_and_b64 s[72:73], vcc, exec
	s_cselect_b32 s69, s64, s66
	s_cselect_b32 s71, s52, s65
	s_lshl_b64 s[72:73], s[94:95], 7
	v_cndmask_b32_e32 v2, v138, v0, vcc
	s_add_u32 s72, s71, s72
	s_mov_b32 s71, s95
	s_addc_u32 s73, s69, s73
	v_lshlrev_b64 v[232:233], 1, v[2:3]
	s_lshl_b64 s[70:71], s[70:71], 7
	v_lshl_add_u64 v[234:235], s[72:73], 0, v[232:233]
	s_add_u32 s72, s72, s70
	s_mov_b32 m0, s42
	s_addc_u32 s73, s73, s71
	s_barrier
	ds_read_b128 v[180:183], v144 offset:16384
	ds_read_b128 v[184:187], v144 offset:17408
	ds_read_b128 v[188:191], v145 offset:16384
	ds_read_b128 v[192:195], v145 offset:17408
	ds_read_b128 v[196:199], v159 offset:16384
	ds_read_b128 v[200:203], v159 offset:17408
	ds_read_b128 v[204:207], v160 offset:16384
	ds_read_b128 v[208:211], v160 offset:17408
	global_load_lds_dwordx4 v[234:235], off
	v_lshl_add_u64 v[234:235], s[72:73], 0, v[232:233]
	s_mov_b32 m0, s39
	s_nop 0
	global_load_lds_dwordx4 v[234:235], off
	s_barrier
	s_waitcnt lgkmcnt(0)
	s_waitcnt lgkmcnt(0)
	v_mfma_f32_16x16x32_bf16 v[64:67], v[164:167], v[180:183], v[64:67]
	v_mfma_f32_16x16x32_bf16 v[60:63], v[172:175], v[180:183], v[60:63]
	v_mfma_f32_16x16x32_bf16 v[56:59], v[164:167], v[188:191], v[56:59]
	v_mfma_f32_16x16x32_bf16 v[52:55], v[172:175], v[188:191], v[52:55]
	v_mfma_f32_16x16x32_bf16 v[40:43], v[164:167], v[196:199], v[40:43]
	v_mfma_f32_16x16x32_bf16 v[36:39], v[172:175], v[196:199], v[36:39]
	v_mfma_f32_16x16x32_bf16 v[24:27], v[164:167], v[204:207], v[24:27]
	v_mfma_f32_16x16x32_bf16 v[20:23], v[172:175], v[204:207], v[20:23]
	v_mfma_f32_16x16x32_bf16 v[64:67], v[168:171], v[184:187], v[64:67]
	v_mfma_f32_16x16x32_bf16 v[60:63], v[176:179], v[184:187], v[60:63]
	v_mfma_f32_16x16x32_bf16 v[56:59], v[168:171], v[192:195], v[56:59]
	v_mfma_f32_16x16x32_bf16 v[52:55], v[176:179], v[192:195], v[52:55]
	v_mfma_f32_16x16x32_bf16 v[40:43], v[168:171], v[200:203], v[40:43]
	v_mfma_f32_16x16x32_bf16 v[36:39], v[176:179], v[200:203], v[36:39]
	v_mfma_f32_16x16x32_bf16 v[24:27], v[168:171], v[208:211], v[24:27]
	v_mfma_f32_16x16x32_bf16 v[20:23], v[176:179], v[208:211], v[20:23]
	s_barrier
	s_add_u32 s2, s2, s0
	s_addc_u32 s3, s3, s1
	v_lshl_add_u64 v[234:235], s[2:3], 0, v[136:137]
	s_add_u32 s2, s2, s0
	s_mov_b32 m0, s45
	s_addc_u32 s3, s3, s1
	global_load_lds_dwordx4 v[234:235], off
	v_lshl_add_u64 v[236:237], s[2:3], 0, v[136:137]
	s_mov_b32 m0, s46
	s_nop 0
	global_load_lds_dwordx4 v[236:237], off
	s_waitcnt vmcnt(6)
	s_barrier
	v_mfma_f32_16x16x32_bf16 v[48:51], v[212:215], v[180:183], v[48:51]
	v_mfma_f32_16x16x32_bf16 v[44:47], v[220:223], v[180:183], v[44:47]
	v_mfma_f32_16x16x32_bf16 v[32:35], v[212:215], v[188:191], v[32:35]
	v_mfma_f32_16x16x32_bf16 v[28:31], v[220:223], v[188:191], v[28:31]
	v_mfma_f32_16x16x32_bf16 v[16:19], v[212:215], v[196:199], v[16:19]
	v_mfma_f32_16x16x32_bf16 v[12:15], v[220:223], v[196:199], v[12:15]
	v_mfma_f32_16x16x32_bf16 v[8:11], v[212:215], v[204:207], v[8:11]
	v_mfma_f32_16x16x32_bf16 v[4:7], v[220:223], v[204:207], v[4:7]
	v_mfma_f32_16x16x32_bf16 v[48:51], v[216:219], v[184:187], v[48:51]
	v_mfma_f32_16x16x32_bf16 v[44:47], v[224:227], v[184:187], v[44:47]
	v_mfma_f32_16x16x32_bf16 v[32:35], v[216:219], v[192:195], v[32:35]
	v_mfma_f32_16x16x32_bf16 v[28:31], v[224:227], v[192:195], v[28:31]
	v_mfma_f32_16x16x32_bf16 v[16:19], v[216:219], v[200:203], v[16:19]
	v_mfma_f32_16x16x32_bf16 v[12:15], v[224:227], v[200:203], v[12:15]
	v_mfma_f32_16x16x32_bf16 v[8:11], v[216:219], v[208:211], v[8:11]
	v_mfma_f32_16x16x32_bf16 v[4:7], v[224:227], v[208:211], v[4:7]
	s_barrier
	ds_read_b128 v[164:167], v162
	ds_read_b128 v[168:171], v162 offset:1024
	ds_read_b128 v[172:175], v162 offset:2048
	ds_read_b128 v[176:179], v162 offset:3072
	s_add_u32 s2, s72, s70
	s_addc_u32 s3, s73, s71
	v_lshl_add_u64 v[212:213], s[2:3], 0, v[232:233]
	s_add_u32 s2, s2, s70
	s_mov_b32 m0, s47
	s_addc_u32 s3, s3, s71
	ds_read_b128 v[180:183], v144 offset:32768
	ds_read_b128 v[184:187], v144 offset:33792
	ds_read_b128 v[188:191], v145 offset:32768
	ds_read_b128 v[192:195], v145 offset:33792
	ds_read_b128 v[196:199], v159 offset:32768
	ds_read_b128 v[200:203], v159 offset:33792
	ds_read_b128 v[204:207], v160 offset:32768
	ds_read_b128 v[208:211], v160 offset:33792
	global_load_lds_dwordx4 v[212:213], off
	v_lshl_add_u64 v[212:213], s[2:3], 0, v[232:233]
	s_mov_b32 m0, s48
	s_nop 0
	global_load_lds_dwordx4 v[212:213], off
	s_waitcnt lgkmcnt(8)
	s_barrier
; #define LDA(dst, b, h) for (int m = 0; m < 4; ++m) for (int k = 0; k < 2; ++k) \
;     dst[m][k] = *reinterpret_cast<const bf16x8*>(SA(b, h) + lds_byte(wr * 64 + m * 16 + fr, k * 32 + fq * 8))
; #define LDB(dst, b, h) for (int n = 0; n < 2; ++n) for (int k = 0; k < 2; ++k) \
;     dst[n][k] = *reinterpret_cast<const bf16x8*>(SB(b, h) + lds_byte(wc * 32 + n * 16 + fr, k * 32 + fq * 8))
; #define MMA(ai, bj, At_, Bt_) do { __builtin_amdgcn_s_setprio(1); \
;     for (int m = 0; m < 4; ++m) for (int n = 0; n < 2; ++n) for (int k = 0; k < 2; ++k) \
;       acc[ai][bj][m][n] = __builtin_amdgcn_mfma_f32_16x16x32_bf16(Bt_[n][k], At_[m][k], acc[ai][bj][m][n], 0, 0, 0); \
;     __builtin_amdgcn_s_setprio(0); } while (0)
; #define WAIT_V(n) asm volatile("s_waitcnt vmcnt(" #n ")" ::: "memory")
; #define WAIT_L(n) asm volatile("s_waitcnt lgkmcnt(" #n ")" ::: "memory")
; #define BAR __builtin_amdgcn_s_barrier()
; #define SCHED __builtin_amdgcn_sched_barrier(0)
; #define STG(P, PTR, LD, O0) do { const bf16_t* _g = (PTR); \
;     __builtin_amdgcn_global_load_lds((const unsigned*)(_g + O0), (lds_u32*)((P) + swave * 1024), 16, 0, 0); \
;     __builtin_amdgcn_global_load_lds((const unsigned*)(_g + (size_t)64 * (LD) + O0), (lds_u32*)((P) + swave * 1024 + 8192), 16, 0, 0); } while (0)
; #define LDA(dst, b, h) for (int m = 0; m < 4; ++m) for (int k = 0; k < 2; ++k) \
;     dst[m][k] = *reinterpret_cast<const bf16x8*>(SA(b, h) + lds_byte(wr * 64 + m * 16 + fr, k * 32 + fq * 8))
; #define LDB(dst, b, h) for (int n = 0; n < 2; ++n) for (int k = 0; k < 2; ++k) \
;     dst[n][k] = *reinterpret_cast<const bf16x8*>(SB(b, h) + lds_byte(wc * 32 + n * 16 + fr, k * 32 + fq * 8))
; #define WAIT_V(n) asm volatile("s_waitcnt vmcnt(" #n ")" ::: "memory")
; #define WAIT_L(n) asm volatile("s_waitcnt lgkmcnt(" #n ")" ::: "memory")
; __device__ __forceinline__ void gemm_stream(int swave, const GemmJob& J, char* shm, int vb, int G) {
;     ...
;       LDB(B0, 1, 0); SCHED; LDA(At, 1, 0); STGA(SA(0, 1), xA, xA1, k2, 1);
;       WAIT_L(8); BAR; WAIT_L(0); MMA(0, 0, At, B0); BAR; SCHED;
;       LDB(B1, 1, 1); STG(SB(1, 0), b3, ldb, offB0);
;       BAR; WAIT_L(0); MMA(0, 1, At, B1); BAR;
;       LDA(At, 1, 1); STGA(SA(1, 0), xA, xA1, k2 + 1, 0);
;       BAR; WAIT_L(0); MMA(1, 0, At, B0); BAR; SCHED;
;       STG(SB(1, 1), b3 + hB, ldb, offB0);
;       WAIT_V(6); BAR; MMA(1, 1, At, B1); BAR;
	s_waitcnt lgkmcnt(0)
	s_waitcnt lgkmcnt(0)
	v_mfma_f32_16x16x32_bf16 v[128:131], v[164:167], v[180:183], v[128:131]
	v_mfma_f32_16x16x32_bf16 v[124:127], v[172:175], v[180:183], v[124:127]
	v_mfma_f32_16x16x32_bf16 v[120:123], v[164:167], v[188:191], v[120:123]
	v_mfma_f32_16x16x32_bf16 v[116:119], v[172:175], v[188:191], v[116:119]
	v_mfma_f32_16x16x32_bf16 v[104:107], v[164:167], v[196:199], v[104:107]
	v_mfma_f32_16x16x32_bf16 v[100:103], v[172:175], v[196:199], v[100:103]
	v_mfma_f32_16x16x32_bf16 v[88:91], v[164:167], v[204:207], v[88:91]
	v_mfma_f32_16x16x32_bf16 v[84:87], v[172:175], v[204:207], v[84:87]
	v_mfma_f32_16x16x32_bf16 v[128:131], v[168:171], v[184:187], v[128:131]
	v_mfma_f32_16x16x32_bf16 v[124:127], v[176:179], v[184:187], v[124:127]
	v_mfma_f32_16x16x32_bf16 v[120:123], v[168:171], v[192:195], v[120:123]
	v_mfma_f32_16x16x32_bf16 v[116:119], v[176:179], v[192:195], v[116:119]
	v_mfma_f32_16x16x32_bf16 v[104:107], v[168:171], v[200:203], v[104:107]
	v_mfma_f32_16x16x32_bf16 v[100:103], v[176:179], v[200:203], v[100:103]
	v_mfma_f32_16x16x32_bf16 v[88:91], v[168:171], v[208:211], v[88:91]
	v_mfma_f32_16x16x32_bf16 v[84:87], v[176:179], v[208:211], v[84:87]
	s_barrier
	v_lshl_add_u64 v[228:229], v[228:229], 0, s[22:23]
	s_add_i32 m0, s42, 0x18000
	ds_read_b128 v[212:215], v163
	ds_read_b128 v[216:219], v163 offset:1024
	ds_read_b128 v[220:223], v163 offset:2048
	ds_read_b128 v[224:227], v163 offset:3072
	global_load_lds_dwordx4 v[228:229], off
	v_lshl_add_u64 v[228:229], v[230:231], 0, s[22:23]
	s_add_i32 m0, s42, 0x1a000
	s_nop 0
	global_load_lds_dwordx4 v[228:229], off
	s_barrier
	s_waitcnt lgkmcnt(0)
	s_waitcnt lgkmcnt(0)
	v_mfma_f32_16x16x32_bf16 v[112:115], v[212:215], v[180:183], v[112:115]
	v_mfma_f32_16x16x32_bf16 v[108:111], v[220:223], v[180:183], v[108:111]
	v_mfma_f32_16x16x32_bf16 v[96:99], v[212:215], v[188:191], v[96:99]
	v_mfma_f32_16x16x32_bf16 v[92:95], v[220:223], v[188:191], v[92:95]
	v_mfma_f32_16x16x32_bf16 v[80:83], v[212:215], v[196:199], v[80:83]
	v_mfma_f32_16x16x32_bf16 v[76:79], v[220:223], v[196:199], v[76:79]
	v_mfma_f32_16x16x32_bf16 v[72:75], v[212:215], v[204:207], v[72:75]
	v_mfma_f32_16x16x32_bf16 v[68:71], v[220:223], v[204:207], v[68:71]
	v_mfma_f32_16x16x32_bf16 v[112:115], v[216:219], v[184:187], v[112:115]
	v_mfma_f32_16x16x32_bf16 v[108:111], v[224:227], v[184:187], v[108:111]
	v_mfma_f32_16x16x32_bf16 v[96:99], v[216:219], v[192:195], v[96:99]
	v_mfma_f32_16x16x32_bf16 v[92:95], v[224:227], v[192:195], v[92:95]
	v_mfma_f32_16x16x32_bf16 v[80:83], v[216:219], v[200:203], v[80:83]
	v_mfma_f32_16x16x32_bf16 v[76:79], v[224:227], v[200:203], v[76:79]
	v_mfma_f32_16x16x32_bf16 v[72:75], v[216:219], v[208:211], v[72:75]
	v_mfma_f32_16x16x32_bf16 v[68:71], v[224:227], v[208:211], v[68:71]
	s_or_b32 s68, s68, 1
	s_cmp_lt_u32 s68, s36
	s_cselect_b64 vcc, -1, 0
	s_and_b64 s[2:3], vcc, exec
	s_cselect_b32 s69, s38, s37
	s_sub_i32 s2, s68, s36
	s_min_u32 s94, s68, s2
	s_and_b64 s[2:3], vcc, exec
	s_cselect_b32 s64, s64, s66
	s_cselect_b32 s52, s52, s65
	s_lshl_b64 s[2:3], s[94:95], 7
	v_cndmask_b32_e32 v2, v138, v0, vcc
	s_add_u32 s2, s52, s2
	s_addc_u32 s3, s64, s3
	v_lshlrev_b64 v[228:229], 1, v[2:3]
	s_lshl_b32 s52, s69, 7
	v_lshl_add_u64 v[230:231], s[2:3], 0, v[228:229]
	s_add_u32 s2, s2, s52
	s_mov_b32 m0, s54
	s_addc_u32 s3, s3, 0
	s_barrier
	ds_read_b128 v[180:183], v144 offset:49152
	ds_read_b128 v[184:187], v144 offset:50176
	ds_read_b128 v[188:191], v145 offset:49152
	ds_read_b128 v[192:195], v145 offset:50176
	ds_read_b128 v[196:199], v159 offset:49152
	ds_read_b128 v[200:203], v159 offset:50176
	ds_read_b128 v[204:207], v160 offset:49152
	ds_read_b128 v[208:211], v160 offset:50176
	global_load_lds_dwordx4 v[230:231], off
	v_lshl_add_u64 v[228:229], s[2:3], 0, v[228:229]
	s_mov_b32 m0, s55
	s_nop 0
	global_load_lds_dwordx4 v[228:229], off
	s_barrier
	s_waitcnt lgkmcnt(0)
	s_waitcnt lgkmcnt(0)
	v_mfma_f32_16x16x32_bf16 v[64:67], v[164:167], v[180:183], v[64:67]
	v_mfma_f32_16x16x32_bf16 v[60:63], v[172:175], v[180:183], v[60:63]
	v_mfma_f32_16x16x32_bf16 v[56:59], v[164:167], v[188:191], v[56:59]
	v_mfma_f32_16x16x32_bf16 v[52:55], v[172:175], v[188:191], v[52:55]
	v_mfma_f32_16x16x32_bf16 v[40:43], v[164:167], v[196:199], v[40:43]
	v_mfma_f32_16x16x32_bf16 v[36:39], v[172:175], v[196:199], v[36:39]
	v_mfma_f32_16x16x32_bf16 v[24:27], v[164:167], v[204:207], v[24:27]
	v_mfma_f32_16x16x32_bf16 v[20:23], v[172:175], v[204:207], v[20:23]
	v_mfma_f32_16x16x32_bf16 v[64:67], v[168:171], v[184:187], v[64:67]
	v_mfma_f32_16x16x32_bf16 v[60:63], v[176:179], v[184:187], v[60:63]
	v_mfma_f32_16x16x32_bf16 v[56:59], v[168:171], v[192:195], v[56:59]
	v_mfma_f32_16x16x32_bf16 v[52:55], v[176:179], v[192:195], v[52:55]
	v_mfma_f32_16x16x32_bf16 v[40:43], v[168:171], v[200:203], v[40:43]
	v_mfma_f32_16x16x32_bf16 v[36:39], v[176:179], v[200:203], v[36:39]
	v_mfma_f32_16x16x32_bf16 v[24:27], v[168:171], v[208:211], v[24:27]
	v_mfma_f32_16x16x32_bf16 v[20:23], v[176:179], v[208:211], v[20:23]
	s_barrier
	v_lshl_add_u64 v[164:165], v[234:235], 0, s[22:23]
	s_add_i32 m0, s42, 0x1c000
	s_nop 0
	global_load_lds_dwordx4 v[164:165], off
	v_lshl_add_u64 v[164:165], v[236:237], 0, s[22:23]
	s_add_i32 m0, s42, 0x1e000
	s_nop 0
	global_load_lds_dwordx4 v[164:165], off
	s_waitcnt vmcnt(6)
	s_barrier
; __device__ __forceinline__ unsigned pk2(float lo, float hi) { f32x2_t v = {lo, hi}; bf16x2_t b = __builtin_convertvector(v, bf16x2_t); return __builtin_bit_cast(unsigned, b); }
; #define MMA(ai, bj, At_, Bt_) do { __builtin_amdgcn_s_setprio(1); \
;     for (int m = 0; m < 4; ++m) for (int n = 0; n < 2; ++n) for (int k = 0; k < 2; ++k) \
;       acc[ai][bj][m][n] = __builtin_amdgcn_mfma_f32_16x16x32_bf16(Bt_[n][k], At_[m][k], acc[ai][bj][m][n], 0, 0, 0); \
;     __builtin_amdgcn_s_setprio(0); } while (0)
; #define WAIT_V(n) asm volatile("s_waitcnt vmcnt(" #n ")" ::: "memory")
; #define BAR __builtin_amdgcn_s_barrier()
; #define MMA(ai, bj, At_, Bt_) do { __builtin_amdgcn_s_setprio(1); \
;     for (int m = 0; m < 4; ++m) for (int n = 0; n < 2; ++n) for (int k = 0; k < 2; ++k) \
;       acc[ai][bj][m][n] = __builtin_amdgcn_mfma_f32_16x16x32_bf16(Bt_[n][k], At_[m][k], acc[ai][bj][m][n], 0, 0, 0); \
;     __builtin_amdgcn_s_setprio(0); } while (0)
; #define WAIT_V(n) asm volatile("s_waitcnt vmcnt(" #n ")" ::: "memory")
; #define BAR __builtin_amdgcn_s_barrier()
; __device__ __forceinline__ void gemm_stream(int swave, const GemmJob& J, char* shm, int vb, int G) {
;     ...
;       WAIT_V(6); BAR; MMA(1, 1, At, B1); BAR;
;     }
;     {
;       bf16_t* C = (bf16_t*)((char*)J.c0 + (size_t)cg * J.strideC);
; #pragma unroll
;       for (int ai = 0; ai < 2; ++ai)
; #pragma unroll
;         for (int m = 0; m < 4; ++m)
; #pragma unroll
;           for (int bj = 0; bj < 2; ++bj) {
;             const f32x4 v0 = acc[ai][bj][m][0], v1 = acc[ai][bj][m][1];
;             uint4 o; o.x = pk2(v0[0], v0[1]); o.y = pk2(v0[2], v0[3]); o.z = pk2(v1[0], v1[1]); o.w = pk2(v1[2], v1[3]);
;             *(uint4*)(C + (size_t)(cbrow + ai * 128 + wr * 64 + m * 16 + fr) * J.ldc + cbcol + bj * 128 + wc * 32 + fq * 8) = o;
;           }
	v_mfma_f32_16x16x32_bf16 v[48:51], v[212:215], v[180:183], v[48:51]
	v_mfma_f32_16x16x32_bf16 v[44:47], v[220:223], v[180:183], v[44:47]
	v_mfma_f32_16x16x32_bf16 v[32:35], v[212:215], v[188:191], v[32:35]
	v_mfma_f32_16x16x32_bf16 v[28:31], v[220:223], v[188:191], v[28:31]
	v_mfma_f32_16x16x32_bf16 v[16:19], v[212:215], v[196:199], v[16:19]
	v_mfma_f32_16x16x32_bf16 v[12:15], v[220:223], v[196:199], v[12:15]
	v_mfma_f32_16x16x32_bf16 v[8:11], v[212:215], v[204:207], v[8:11]
	v_mfma_f32_16x16x32_bf16 v[4:7], v[220:223], v[204:207], v[4:7]
	v_mfma_f32_16x16x32_bf16 v[48:51], v[216:219], v[184:187], v[48:51]
	v_mfma_f32_16x16x32_bf16 v[44:47], v[224:227], v[184:187], v[44:47]
	v_mfma_f32_16x16x32_bf16 v[32:35], v[216:219], v[192:195], v[32:35]
	v_mfma_f32_16x16x32_bf16 v[28:31], v[224:227], v[192:195], v[28:31]
	v_mfma_f32_16x16x32_bf16 v[16:19], v[216:219], v[200:203], v[16:19]
	v_mfma_f32_16x16x32_bf16 v[12:15], v[224:227], v[200:203], v[12:15]
	v_mfma_f32_16x16x32_bf16 v[8:11], v[216:219], v[208:211], v[8:11]
	v_mfma_f32_16x16x32_bf16 v[4:7], v[224:227], v[208:211], v[4:7]
	s_add_i32 s29, s29, 2
	s_add_u32 s20, s20, 0x100
	s_addc_u32 s21, s21, 0
	s_cmp_ge_u32 s33, s49
	s_mov_b32 s2, s33
	s_barrier
	s_cbranch_scc0 .LBB0_729
	v_add_u32_e32 v164, s5, v1
	s_ashr_i32 s5, s4, 31
	s_lshl_b64 s[2:3], s[4:5], 1
	v_ashrrev_i32_e32 v2, 31, v164
	s_add_u32 s2, s50, s2
	v_cvt_pk_bf16_f32 v128, v128, v129
	v_cvt_pk_bf16_f32 v129, v130, v131
	v_cvt_pk_bf16_f32 v130, v124, v125
	v_mul_lo_u32 v2, v2, s18
	v_mad_u64_u32 v[124:125], s[4:5], v164, s18, 0
	s_addc_u32 s3, s51, s3
	v_add_u32_e32 v125, v125, v2
	v_lshl_add_u64 v[124:125], v[124:125], 1, s[2:3]
	v_mov_b32_e32 v141, v3
	v_lshl_add_u64 v[124:125], v[124:125], 0, v[140:141]
	v_mov_b32_e32 v143, v3
	v_lshl_add_u64 v[124:125], v[124:125], 0, v[142:143]
	s_lshl_b32 s2, s18, 5
	s_mov_b32 s3, 0
	s_mul_i32 s4, s18, 0xa0
	s_mov_b32 s5, 0
	v_cvt_pk_bf16_f32 v112, v112, v113
	v_cvt_pk_bf16_f32 v113, v114, v115
	v_cvt_pk_bf16_f32 v114, v108, v109
	v_cvt_pk_bf16_f32 v115, v110, v111
	global_store_dwordx4 v[124:125], v[112:115], off offset:256
	v_cvt_pk_bf16_f32 v131, v126, v127
	v_cvt_pk_bf16_f32 v96, v96, v97
	v_lshl_add_u64 v[112:113], v[124:125], 0, s[2:3]
	v_cvt_pk_bf16_f32 v97, v98, v99
	v_cvt_pk_bf16_f32 v98, v92, v93
	v_cvt_pk_bf16_f32 v99, v94, v95
	global_store_dwordx4 v[124:125], v[128:131], off
	global_store_dwordx4 v[112:113], v[96:99], off offset:256
	v_cvt_pk_bf16_f32 v108, v120, v121
	v_cvt_pk_bf16_f32 v109, v122, v123
	v_lshl_add_u64 v[96:97], v[112:113], 0, s[2:3]
	v_cvt_pk_bf16_f32 v110, v116, v117
	v_cvt_pk_bf16_f32 v111, v118, v119
	v_cvt_pk_bf16_f32 v80, v80, v81
	v_cvt_pk_bf16_f32 v81, v82, v83
	v_cvt_pk_bf16_f32 v82, v76, v77
	v_cvt_pk_bf16_f32 v83, v78, v79
	global_store_dwordx4 v[112:113], v[108:111], off
	global_store_dwordx4 v[96:97], v[80:83], off offset:256
	v_cvt_pk_bf16_f32 v64, v64, v65
	v_cvt_pk_bf16_f32 v65, v66, v67
	v_lshl_add_u64 v[80:81], v[96:97], 0, s[2:3]
	v_cvt_pk_bf16_f32 v66, v60, v61
	v_lshl_add_u64 v[60:61], v[80:81], 0, s[4:5]
	v_cvt_pk_bf16_f32 v72, v72, v73
	v_cvt_pk_bf16_f32 v73, v74, v75
	v_cvt_pk_bf16_f32 v74, v68, v69
	v_cvt_pk_bf16_f32 v67, v62, v63
	v_cvt_pk_bf16_f32 v92, v104, v105
	v_cvt_pk_bf16_f32 v93, v106, v107
	v_cvt_pk_bf16_f32 v94, v100, v101
	v_cvt_pk_bf16_f32 v95, v102, v103
	v_cvt_pk_bf16_f32 v76, v88, v89
	v_cvt_pk_bf16_f32 v77, v90, v91
	v_cvt_pk_bf16_f32 v78, v84, v85
	v_cvt_pk_bf16_f32 v79, v86, v87
	v_cvt_pk_bf16_f32 v75, v70, v71
	v_cvt_pk_bf16_f32 v48, v48, v49
	v_cvt_pk_bf16_f32 v49, v50, v51
	v_cvt_pk_bf16_f32 v50, v44, v45
	v_cvt_pk_bf16_f32 v51, v46, v47
	global_store_dwordx4 v[96:97], v[92:95], off
	global_store_dwordx4 v[80:81], v[76:79], off
	global_store_dwordx4 v[80:81], v[72:75], off offset:256
	global_store_dwordx4 v[60:61], v[48:51], off offset:256
	v_cvt_pk_bf16_f32 v32, v32, v33
	v_cvt_pk_bf16_f32 v33, v34, v35
	v_lshl_add_u64 v[48:49], v[60:61], 0, s[2:3]
	v_cvt_pk_bf16_f32 v34, v28, v29
	v_cvt_pk_bf16_f32 v35, v30, v31
	global_store_dwordx4 v[60:61], v[64:67], off
	global_store_dwordx4 v[48:49], v[32:35], off offset:256
	v_cvt_pk_bf16_f32 v44, v56, v57
	v_cvt_pk_bf16_f32 v45, v58, v59
	v_lshl_add_u64 v[32:33], v[48:49], 0, s[2:3]
	v_cvt_pk_bf16_f32 v46, v52, v53
	v_cvt_pk_bf16_f32 v47, v54, v55
	v_cvt_pk_bf16_f32 v16, v16, v17
	v_cvt_pk_bf16_f32 v17, v18, v19
	v_cvt_pk_bf16_f32 v18, v12, v13
	v_cvt_pk_bf16_f32 v19, v14, v15
	global_store_dwordx4 v[48:49], v[44:47], off
	global_store_dwordx4 v[32:33], v[16:19], off offset:256
	v_cvt_pk_bf16_f32 v28, v40, v41
	v_cvt_pk_bf16_f32 v29, v42, v43
	v_lshl_add_u64 v[16:17], v[32:33], 0, s[2:3]
	v_cvt_pk_bf16_f32 v30, v36, v37
	v_cvt_pk_bf16_f32 v31, v38, v39
	v_cvt_pk_bf16_f32 v12, v24, v25
	v_cvt_pk_bf16_f32 v13, v26, v27
	v_cvt_pk_bf16_f32 v14, v20, v21
	v_cvt_pk_bf16_f32 v15, v22, v23
	v_cvt_pk_bf16_f32 v8, v8, v9
	v_cvt_pk_bf16_f32 v9, v10, v11
	v_cvt_pk_bf16_f32 v10, v4, v5
	v_cvt_pk_bf16_f32 v11, v6, v7
	s_and_b64 vcc, exec, s[6:7]
	s_mov_b64 s[2:3], s[14:15]
	s_mov_b64 s[16:17], s[12:13]
	s_mov_b64 s[8:9], s[10:11]
	s_mov_b32 s4, s56
	s_mov_b32 s5, s28
	global_store_dwordx4 v[32:33], v[28:31], off
	global_store_dwordx4 v[16:17], v[12:15], off
	global_store_dwordx4 v[16:17], v[8:11], off offset:256
	s_cbranch_vccz .LBB0_726
	s_waitcnt vmcnt(0)
	s_movk_i32 s66, 0x100
	v_cmp_gt_u32_e32 vcc, s66, v135
	s_and_saveexec_b64 s[0:1], vcc
	s_cbranch_execz .LBB0_733
	s_barrier
